# instruction selection in the VALU-bound gate|up epilogue: 128 copies in front of row_shr DPP moves dropped (the untouched lanes are always overwritten)
# speedup vs baseline: 1.0145x; 1.0145x over previous
; __device__ __forceinline__ float bf_lo(unsigned w) { return __uint_as_float(w << 16); }
; __device__ __forceinline__ float bf_hi(unsigned w) { return __uint_as_float(w & 0xffff0000u); }
;     __device__ __forceinline__ void operator()(const f32x4 (&acc)[2][2][4][2], const Unit& u, int wr, int wc, int fr_in, int fq_in, PG8_LAS unsigned char* lds, int tid_in, int quad = -1) const {
;     ...
;                     const f32x4 w0 = *(const f32x4*)(cw + col + 4 * hf), w1 = *(const f32x4*)(cw + DFF + col + 4 * hf), w2 = *(const f32x4*)(cw + 2 * DFF + col + 4 * hf);
;                     float cur[4], p1[4], p2[4];
; #pragma unroll
;                     for (int k = 0; k < 4; ++k) { cur[k] = acc[ai][0][m][hf][k] * sc;
;                         p1[k] = __int_as_float(__builtin_amdgcn_update_dpp(__float_as_int(cur[k]), __float_as_int(cur[k]), 0x111, 0xf, 0xf, false));
;                         p2[k] = __int_as_float(__builtin_amdgcn_update_dpp(__float_as_int(cur[k]), __float_as_int(cur[k]), 0x112, 0xf, 0xf, false)); }
;                     if (fr < 2) {
;                         const float e0 = bf_lo(h1[2 * hf]), e1 = bf_hi(h1[2 * hf]), e2 = bf_lo(h1[2 * hf + 1]), e3 = bf_hi(h1[2 * hf + 1]);
;                         if (fr == 0) {
;                             p1[0] = e0 * sc1; p1[1] = e1 * sc1; p1[2] = e2 * sc1; p1[3] = e3 * sc1;
;                             p2[0] = bf_lo(h0[2 * hf]) * sc2; p2[1] = bf_hi(h0[2 * hf]) * sc2; p2[2] = bf_lo(h0[2 * hf + 1]) * sc2; p2[3] = bf_hi(h0[2 * hf + 1]) * sc2;
;                         } else { p2[0] = e0 * sc2; p2[1] = e1 * sc2; p2[2] = e2 * sc2; p2[3] = e3 * sc2; }
.LBB0_652:
	s_or_b64 exec, exec, s[24:25]
	v_lshl_add_u32 v168, s46, 7, v132
	v_ashrrev_i32_e32 v169, 31, v168
	s_waitcnt lgkmcnt(3)
	v_lshlrev_b64 v[130:131], 2, v[168:169]
	v_lshl_add_u64 v[170:171], s[60:61], 0, v[130:131]
	v_lshl_add_u64 v[172:173], s[14:15], 0, v[130:131]
	v_lshl_add_u64 v[174:175], s[16:17], 0, v[130:131]
	global_load_dwordx4 v[138:141], v[170:171], off
	global_load_dwordx4 v[134:137], v[172:173], off
	global_load_dwordx4 v[130:133], v[174:175], off
	s_waitcnt lgkmcnt(2)
	v_mul_f32_e32 v221, v126, v207
	v_mul_f32_e32 v220, v127, v207
	v_mul_f32_e32 v219, v128, v207
	v_mul_f32_e32 v218, v129, v207
	v_cmp_ne_u32_e64 s[46:47], 0, v146
	v_mov_b32_dpp v178, v221 row_shr:1 row_mask:0xf bank_mask:0xf
	v_mov_b32_dpp v182, v221 row_shr:2 row_mask:0xf bank_mask:0xf
	v_mov_b32_dpp v179, v220 row_shr:1 row_mask:0xf bank_mask:0xf
	v_mov_b32_dpp v183, v220 row_shr:2 row_mask:0xf bank_mask:0xf
	v_mov_b32_dpp v176, v219 row_shr:1 row_mask:0xf bank_mask:0xf
	v_mov_b32_dpp v180, v219 row_shr:2 row_mask:0xf bank_mask:0xf
	v_mov_b32_dpp v177, v218 row_shr:1 row_mask:0xf bank_mask:0xf
	v_mov_b32_dpp v181, v218 row_shr:2 row_mask:0xf bank_mask:0xf
	s_and_saveexec_b64 s[24:25], s[44:45]
	s_cbranch_execz .LBB0_658
	s_waitcnt lgkmcnt(1)
	v_lshlrev_b32_e32 v126, 16, v152
	v_and_b32_e32 v127, 0xffff0000, v152
	v_lshlrev_b32_e32 v128, 16, v153
	v_and_b32_e32 v129, 0xffff0000, v153
	s_and_saveexec_b64 s[26:27], s[46:47]
	s_xor_b64 s[26:27], exec, s[26:27]
	s_cbranch_execz .LBB0_655
	s_waitcnt lgkmcnt(0)
	v_pk_mul_f32 v[180:181], v[0:1], v[128:129] op_sel_hi:[0,1]
	v_pk_mul_f32 v[182:183], v[0:1], v[126:127] op_sel_hi:[0,1]

; __device__ __forceinline__ float bf_lo(unsigned w) { return __uint_as_float(w << 16); }
; __device__ __forceinline__ float bf_hi(unsigned w) { return __uint_as_float(w & 0xffff0000u); }
;     __device__ __forceinline__ void operator()(const f32x4 (&acc)[2][2][4][2], const Unit& u, int wr, int wc, int fr_in, int fq_in, PG8_LAS unsigned char* lds, int tid_in, int quad = -1) const {
;     ...
;                     const f32x4 w0 = *(const f32x4*)(cw + col + 4 * hf), w1 = *(const f32x4*)(cw + DFF + col + 4 * hf), w2 = *(const f32x4*)(cw + 2 * DFF + col + 4 * hf);
;                     float cur[4], p1[4], p2[4];
; #pragma unroll
;                     for (int k = 0; k < 4; ++k) { cur[k] = acc[ai][0][m][hf][k] * sc;
;                         p1[k] = __int_as_float(__builtin_amdgcn_update_dpp(__float_as_int(cur[k]), __float_as_int(cur[k]), 0x111, 0xf, 0xf, false));
;                         p2[k] = __int_as_float(__builtin_amdgcn_update_dpp(__float_as_int(cur[k]), __float_as_int(cur[k]), 0x112, 0xf, 0xf, false)); }
;                     if (fr < 2) {
;                         const float e0 = bf_lo(h1[2 * hf]), e1 = bf_hi(h1[2 * hf]), e2 = bf_lo(h1[2 * hf + 1]), e3 = bf_hi(h1[2 * hf + 1]);
;                         if (fr == 0) {
;                             p1[0] = e0 * sc1; p1[1] = e1 * sc1; p1[2] = e2 * sc1; p1[3] = e3 * sc1;
;                             p2[0] = bf_lo(h0[2 * hf]) * sc2; p2[1] = bf_hi(h0[2 * hf]) * sc2; p2[2] = bf_lo(h0[2 * hf + 1]) * sc2; p2[3] = bf_hi(h0[2 * hf + 1]) * sc2;
;                         } else { p2[0] = e0 * sc2; p2[1] = e1 * sc2; p2[2] = e2 * sc2; p2[3] = e3 * sc2; }
.LBB0_658:
	s_or_b64 exec, exec, s[24:25]
	s_waitcnt lgkmcnt(1)
	global_load_dwordx4 v[150:153], v[170:171], off offset:16
	global_load_dwordx4 v[146:149], v[172:173], off offset:16
	global_load_dwordx4 v[126:129], v[174:175], off offset:16
	v_mul_f32_e32 v225, v122, v207
	v_mul_f32_e32 v224, v123, v207
	v_mul_f32_e32 v223, v124, v207
	v_mul_f32_e32 v222, v125, v207
	s_waitcnt lgkmcnt(0)
	v_mov_b32_dpp v142, v225 row_shr:1 row_mask:0xf bank_mask:0xf
	v_mov_b32_dpp v186, v225 row_shr:2 row_mask:0xf bank_mask:0xf
	v_mov_b32_dpp v143, v224 row_shr:1 row_mask:0xf bank_mask:0xf
	v_mov_b32_dpp v187, v224 row_shr:2 row_mask:0xf bank_mask:0xf
	v_mov_b32_dpp v122, v223 row_shr:1 row_mask:0xf bank_mask:0xf
	v_mov_b32_dpp v124, v223 row_shr:2 row_mask:0xf bank_mask:0xf
	v_mov_b32_dpp v123, v222 row_shr:1 row_mask:0xf bank_mask:0xf
	v_mov_b32_dpp v125, v222 row_shr:2 row_mask:0xf bank_mask:0xf
	s_and_saveexec_b64 s[24:25], s[44:45]
	s_cbranch_execz .LBB0_664
	v_lshlrev_b32_e32 v188, 16, v154
	v_and_b32_e32 v189, 0xffff0000, v154
	v_lshlrev_b32_e32 v154, 16, v155
	v_and_b32_e32 v155, 0xffff0000, v155
	s_and_saveexec_b64 s[26:27], s[46:47]
	s_xor_b64 s[26:27], exec, s[26:27]
	v_pk_mul_f32 v[124:125], v[0:1], v[154:155] op_sel_hi:[0,1]
	v_pk_mul_f32 v[186:187], v[0:1], v[188:189] op_sel_hi:[0,1]
	s_andn2_saveexec_b64 s[48:49], s[26:27]
	v_lshlrev_b32_e32 v124, 16, v144
	v_and_b32_e32 v125, 0xffff0000, v144
	v_pk_mul_f32 v[186:187], v[0:1], v[124:125] op_sel_hi:[0,1]
	v_lshlrev_b32_e32 v124, 16, v145
	v_and_b32_e32 v125, 0xffff0000, v145
	v_pk_mul_f32 v[122:123], v[184:185], v[154:155] op_sel_hi:[0,1]
	v_pk_mul_f32 v[142:143], v[184:185], v[188:189] op_sel_hi:[0,1]
	v_pk_mul_f32 v[124:125], v[0:1], v[124:125] op_sel_hi:[0,1]
	s_or_b64 exec, exec, s[48:49]

; __device__ __forceinline__ float bf_lo(unsigned w) { return __uint_as_float(w << 16); }
; __device__ __forceinline__ float bf_hi(unsigned w) { return __uint_as_float(w & 0xffff0000u); }
;     __device__ __forceinline__ void operator()(const f32x4 (&acc)[2][2][4][2], const Unit& u, int wr, int wc, int fr_in, int fq_in, PG8_LAS unsigned char* lds, int tid_in, int quad = -1) const {
;     ...
;                     const f32x4 w0 = *(const f32x4*)(cw + col + 4 * hf), w1 = *(const f32x4*)(cw + DFF + col + 4 * hf), w2 = *(const f32x4*)(cw + 2 * DFF + col + 4 * hf);
;                     float cur[4], p1[4], p2[4];
; #pragma unroll
;                     for (int k = 0; k < 4; ++k) { cur[k] = acc[ai][0][m][hf][k] * sc;
;                         p1[k] = __int_as_float(__builtin_amdgcn_update_dpp(__float_as_int(cur[k]), __float_as_int(cur[k]), 0x111, 0xf, 0xf, false));
;                         p2[k] = __int_as_float(__builtin_amdgcn_update_dpp(__float_as_int(cur[k]), __float_as_int(cur[k]), 0x112, 0xf, 0xf, false)); }
;                     if (fr < 2) {
;                         const float e0 = bf_lo(h1[2 * hf]), e1 = bf_hi(h1[2 * hf]), e2 = bf_lo(h1[2 * hf + 1]), e3 = bf_hi(h1[2 * hf + 1]);
;                         if (fr == 0) {
;                             p1[0] = e0 * sc1; p1[1] = e1 * sc1; p1[2] = e2 * sc1; p1[3] = e3 * sc1;
;                             p2[0] = bf_lo(h0[2 * hf]) * sc2; p2[1] = bf_hi(h0[2 * hf]) * sc2; p2[2] = bf_lo(h0[2 * hf + 1]) * sc2; p2[3] = bf_hi(h0[2 * hf + 1]) * sc2;
;                         } else { p2[0] = e0 * sc2; p2[1] = e1 * sc2; p2[2] = e2 * sc2; p2[3] = e3 * sc2; }
.LBB0_671:
	s_or_b64 exec, exec, s[48:49]
	global_load_dwordx4 v[122:125], v[170:171], off
	global_load_dwordx4 v[118:121], v[172:173], off
	global_load_dwordx4 v[114:117], v[174:175], off
	s_waitcnt lgkmcnt(2)
	v_mul_f32_e32 v177, v110, v149
	v_mul_f32_e32 v176, v111, v149
	v_mul_f32_e32 v155, v112, v149
	v_mul_f32_e32 v154, v113, v149
	v_mov_b32_dpp v142, v177 row_shr:1 row_mask:0xf bank_mask:0xf
	v_mov_b32_dpp v146, v177 row_shr:2 row_mask:0xf bank_mask:0xf
	v_mov_b32_dpp v143, v176 row_shr:1 row_mask:0xf bank_mask:0xf
	v_mov_b32_dpp v147, v176 row_shr:2 row_mask:0xf bank_mask:0xf
	v_mov_b32_dpp v140, v155 row_shr:1 row_mask:0xf bank_mask:0xf
	v_mov_b32_dpp v144, v155 row_shr:2 row_mask:0xf bank_mask:0xf
	v_mov_b32_dpp v141, v154 row_shr:1 row_mask:0xf bank_mask:0xf
	v_mov_b32_dpp v145, v154 row_shr:2 row_mask:0xf bank_mask:0xf
	s_and_saveexec_b64 s[48:49], s[44:45]
	s_cbranch_execz .LBB0_677
	s_waitcnt lgkmcnt(1)
	v_lshlrev_b32_e32 v110, 16, v136
	v_and_b32_e32 v111, 0xffff0000, v136
	v_lshlrev_b32_e32 v112, 16, v137
	v_and_b32_e32 v113, 0xffff0000, v137
	s_and_saveexec_b64 s[26:27], s[46:47]
	s_xor_b64 s[26:27], exec, s[26:27]
	s_cbranch_execz .LBB0_674
	s_waitcnt lgkmcnt(0)
	v_pk_mul_f32 v[144:145], v[0:1], v[112:113] op_sel_hi:[0,1]
	v_pk_mul_f32 v[146:147], v[0:1], v[110:111] op_sel_hi:[0,1]

; __device__ __forceinline__ float bf_lo(unsigned w) { return __uint_as_float(w << 16); }
; __device__ __forceinline__ float bf_hi(unsigned w) { return __uint_as_float(w & 0xffff0000u); }
;     __device__ __forceinline__ void operator()(const f32x4 (&acc)[2][2][4][2], const Unit& u, int wr, int wc, int fr_in, int fq_in, PG8_LAS unsigned char* lds, int tid_in, int quad = -1) const {
;     ...
;                     const f32x4 w0 = *(const f32x4*)(cw + col + 4 * hf), w1 = *(const f32x4*)(cw + DFF + col + 4 * hf), w2 = *(const f32x4*)(cw + 2 * DFF + col + 4 * hf);
;                     float cur[4], p1[4], p2[4];
; #pragma unroll
;                     for (int k = 0; k < 4; ++k) { cur[k] = acc[ai][0][m][hf][k] * sc;
;                         p1[k] = __int_as_float(__builtin_amdgcn_update_dpp(__float_as_int(cur[k]), __float_as_int(cur[k]), 0x111, 0xf, 0xf, false));
;                         p2[k] = __int_as_float(__builtin_amdgcn_update_dpp(__float_as_int(cur[k]), __float_as_int(cur[k]), 0x112, 0xf, 0xf, false)); }
;                     if (fr < 2) {
;                         const float e0 = bf_lo(h1[2 * hf]), e1 = bf_hi(h1[2 * hf]), e2 = bf_lo(h1[2 * hf + 1]), e3 = bf_hi(h1[2 * hf + 1]);
;                         if (fr == 0) {
;                             p1[0] = e0 * sc1; p1[1] = e1 * sc1; p1[2] = e2 * sc1; p1[3] = e3 * sc1;
;                             p2[0] = bf_lo(h0[2 * hf]) * sc2; p2[1] = bf_hi(h0[2 * hf]) * sc2; p2[2] = bf_lo(h0[2 * hf + 1]) * sc2; p2[3] = bf_hi(h0[2 * hf + 1]) * sc2;
;                         } else { p2[0] = e0 * sc2; p2[1] = e1 * sc2; p2[2] = e2 * sc2; p2[3] = e3 * sc2; }
.LBB0_677:
	s_or_b64 exec, exec, s[48:49]
	s_waitcnt lgkmcnt(1)
	global_load_dwordx4 v[134:137], v[170:171], off offset:16
	global_load_dwordx4 v[130:133], v[172:173], off offset:16
	global_load_dwordx4 v[110:113], v[174:175], off offset:16
	v_mul_f32_e32 v182, v106, v149
	v_mul_f32_e32 v181, v107, v149
	v_mul_f32_e32 v180, v108, v149
	v_mul_f32_e32 v179, v109, v149
	s_waitcnt lgkmcnt(0)
	v_mov_b32_dpp v126, v182 row_shr:1 row_mask:0xf bank_mask:0xf
	v_mov_b32_dpp v150, v182 row_shr:2 row_mask:0xf bank_mask:0xf
	v_mov_b32_dpp v127, v181 row_shr:1 row_mask:0xf bank_mask:0xf
	v_mov_b32_dpp v151, v181 row_shr:2 row_mask:0xf bank_mask:0xf
	v_mov_b32_dpp v106, v180 row_shr:1 row_mask:0xf bank_mask:0xf
	v_mov_b32_dpp v108, v180 row_shr:2 row_mask:0xf bank_mask:0xf
	v_mov_b32_dpp v107, v179 row_shr:1 row_mask:0xf bank_mask:0xf
	v_mov_b32_dpp v109, v179 row_shr:2 row_mask:0xf bank_mask:0xf
	s_and_saveexec_b64 s[48:49], s[44:45]
	s_cbranch_execz .LBB0_683
	v_lshlrev_b32_e32 v152, 16, v138
	v_and_b32_e32 v153, 0xffff0000, v138
	v_lshlrev_b32_e32 v138, 16, v139
	v_and_b32_e32 v139, 0xffff0000, v139
	s_and_saveexec_b64 s[26:27], s[46:47]
	s_xor_b64 s[26:27], exec, s[26:27]
	v_pk_mul_f32 v[108:109], v[0:1], v[138:139] op_sel_hi:[0,1]
	v_pk_mul_f32 v[150:151], v[0:1], v[152:153] op_sel_hi:[0,1]
	s_andn2_saveexec_b64 vcc, s[26:27]
	v_lshlrev_b32_e32 v108, 16, v128
	v_and_b32_e32 v109, 0xffff0000, v128
	v_pk_mul_f32 v[150:151], v[0:1], v[108:109] op_sel_hi:[0,1]
	v_lshlrev_b32_e32 v108, 16, v129
	v_and_b32_e32 v109, 0xffff0000, v129
	v_pk_mul_f32 v[106:107], v[148:149], v[138:139] op_sel_hi:[0,1]
	v_pk_mul_f32 v[126:127], v[148:149], v[152:153] op_sel_hi:[0,1]
	v_pk_mul_f32 v[108:109], v[0:1], v[108:109] op_sel_hi:[0,1]
	s_or_b64 exec, exec, vcc

; __device__ __forceinline__ float bf_lo(unsigned w) { return __uint_as_float(w << 16); }
; __device__ __forceinline__ float bf_hi(unsigned w) { return __uint_as_float(w & 0xffff0000u); }
;     __device__ __forceinline__ void operator()(const f32x4 (&acc)[2][2][4][2], const Unit& u, int wr, int wc, int fr_in, int fq_in, PG8_LAS unsigned char* lds, int tid_in, int quad = -1) const {
;     ...
;                     const f32x4 w0 = *(const f32x4*)(cw + col + 4 * hf), w1 = *(const f32x4*)(cw + DFF + col + 4 * hf), w2 = *(const f32x4*)(cw + 2 * DFF + col + 4 * hf);
;                     float cur[4], p1[4], p2[4];
; #pragma unroll
;                     for (int k = 0; k < 4; ++k) { cur[k] = acc[ai][0][m][hf][k] * sc;
;                         p1[k] = __int_as_float(__builtin_amdgcn_update_dpp(__float_as_int(cur[k]), __float_as_int(cur[k]), 0x111, 0xf, 0xf, false));
;                         p2[k] = __int_as_float(__builtin_amdgcn_update_dpp(__float_as_int(cur[k]), __float_as_int(cur[k]), 0x112, 0xf, 0xf, false)); }
;                     if (fr < 2) {
;                         const float e0 = bf_lo(h1[2 * hf]), e1 = bf_hi(h1[2 * hf]), e2 = bf_lo(h1[2 * hf + 1]), e3 = bf_hi(h1[2 * hf + 1]);
;                         if (fr == 0) {
;                             p1[0] = e0 * sc1; p1[1] = e1 * sc1; p1[2] = e2 * sc1; p1[3] = e3 * sc1;
;                             p2[0] = bf_lo(h0[2 * hf]) * sc2; p2[1] = bf_hi(h0[2 * hf]) * sc2; p2[2] = bf_lo(h0[2 * hf + 1]) * sc2; p2[3] = bf_hi(h0[2 * hf + 1]) * sc2;
;                         } else { p2[0] = e0 * sc2; p2[1] = e1 * sc2; p2[2] = e2 * sc2; p2[3] = e3 * sc2; }
.LBB0_690:
	s_or_b64 exec, exec, s[50:51]
	global_load_dwordx4 v[106:109], v[170:171], off
	global_load_dwordx4 v[102:105], v[172:173], off
	global_load_dwordx4 v[98:101], v[174:175], off
	s_waitcnt lgkmcnt(2)
	v_mul_f32_e32 v141, v94, v133
	v_mul_f32_e32 v140, v95, v133
	v_mul_f32_e32 v139, v96, v133
	v_mul_f32_e32 v138, v97, v133
	v_mov_b32_dpp v126, v141 row_shr:1 row_mask:0xf bank_mask:0xf
	v_mov_b32_dpp v130, v141 row_shr:2 row_mask:0xf bank_mask:0xf
	v_mov_b32_dpp v127, v140 row_shr:1 row_mask:0xf bank_mask:0xf
	v_mov_b32_dpp v131, v140 row_shr:2 row_mask:0xf bank_mask:0xf
	v_mov_b32_dpp v124, v139 row_shr:1 row_mask:0xf bank_mask:0xf
	v_mov_b32_dpp v128, v139 row_shr:2 row_mask:0xf bank_mask:0xf
	v_mov_b32_dpp v125, v138 row_shr:1 row_mask:0xf bank_mask:0xf
	v_mov_b32_dpp v129, v138 row_shr:2 row_mask:0xf bank_mask:0xf
	s_and_saveexec_b64 s[50:51], s[44:45]
	s_cbranch_execz .LBB0_696
	s_waitcnt lgkmcnt(1)
	v_lshlrev_b32_e32 v94, 16, v120
	v_and_b32_e32 v95, 0xffff0000, v120
	v_lshlrev_b32_e32 v96, 16, v121
	v_and_b32_e32 v97, 0xffff0000, v121
	s_and_saveexec_b64 s[26:27], s[46:47]
	s_xor_b64 s[26:27], exec, s[26:27]
	s_cbranch_execz .LBB0_693
	s_waitcnt lgkmcnt(0)
	v_pk_mul_f32 v[128:129], v[0:1], v[96:97] op_sel_hi:[0,1]
	v_pk_mul_f32 v[130:131], v[0:1], v[94:95] op_sel_hi:[0,1]

; __device__ __forceinline__ float bf_lo(unsigned w) { return __uint_as_float(w << 16); }
; __device__ __forceinline__ float bf_hi(unsigned w) { return __uint_as_float(w & 0xffff0000u); }
;     __device__ __forceinline__ void operator()(const f32x4 (&acc)[2][2][4][2], const Unit& u, int wr, int wc, int fr_in, int fq_in, PG8_LAS unsigned char* lds, int tid_in, int quad = -1) const {
;     ...
;                     const f32x4 w0 = *(const f32x4*)(cw + col + 4 * hf), w1 = *(const f32x4*)(cw + DFF + col + 4 * hf), w2 = *(const f32x4*)(cw + 2 * DFF + col + 4 * hf);
;                     float cur[4], p1[4], p2[4];
; #pragma unroll
;                     for (int k = 0; k < 4; ++k) { cur[k] = acc[ai][0][m][hf][k] * sc;
;                         p1[k] = __int_as_float(__builtin_amdgcn_update_dpp(__float_as_int(cur[k]), __float_as_int(cur[k]), 0x111, 0xf, 0xf, false));
;                         p2[k] = __int_as_float(__builtin_amdgcn_update_dpp(__float_as_int(cur[k]), __float_as_int(cur[k]), 0x112, 0xf, 0xf, false)); }
;                     if (fr < 2) {
;                         const float e0 = bf_lo(h1[2 * hf]), e1 = bf_hi(h1[2 * hf]), e2 = bf_lo(h1[2 * hf + 1]), e3 = bf_hi(h1[2 * hf + 1]);
;                         if (fr == 0) {
;                             p1[0] = e0 * sc1; p1[1] = e1 * sc1; p1[2] = e2 * sc1; p1[3] = e3 * sc1;
;                             p2[0] = bf_lo(h0[2 * hf]) * sc2; p2[1] = bf_hi(h0[2 * hf]) * sc2; p2[2] = bf_lo(h0[2 * hf + 1]) * sc2; p2[3] = bf_hi(h0[2 * hf + 1]) * sc2;
;                         } else { p2[0] = e0 * sc2; p2[1] = e1 * sc2; p2[2] = e2 * sc2; p2[3] = e3 * sc2; }
.LBB0_696:
	s_or_b64 exec, exec, s[50:51]
	s_waitcnt lgkmcnt(1)
	global_load_dwordx4 v[118:121], v[170:171], off offset:16
	global_load_dwordx4 v[114:117], v[172:173], off offset:16
	global_load_dwordx4 v[94:97], v[174:175], off offset:16
	v_mul_f32_e32 v146, v90, v133
	v_mul_f32_e32 v145, v91, v133
	v_mul_f32_e32 v144, v92, v133
	v_mul_f32_e32 v143, v93, v133
	s_waitcnt lgkmcnt(0)
	v_mov_b32_dpp v110, v146 row_shr:1 row_mask:0xf bank_mask:0xf
	v_mov_b32_dpp v134, v146 row_shr:2 row_mask:0xf bank_mask:0xf
	v_mov_b32_dpp v111, v145 row_shr:1 row_mask:0xf bank_mask:0xf
	v_mov_b32_dpp v135, v145 row_shr:2 row_mask:0xf bank_mask:0xf
	v_mov_b32_dpp v90, v144 row_shr:1 row_mask:0xf bank_mask:0xf
	v_mov_b32_dpp v92, v144 row_shr:2 row_mask:0xf bank_mask:0xf
	v_mov_b32_dpp v91, v143 row_shr:1 row_mask:0xf bank_mask:0xf
	v_mov_b32_dpp v93, v143 row_shr:2 row_mask:0xf bank_mask:0xf
	s_and_saveexec_b64 s[50:51], s[44:45]
	s_cbranch_execz .LBB0_702
	v_lshlrev_b32_e32 v136, 16, v122
	v_and_b32_e32 v137, 0xffff0000, v122
	v_lshlrev_b32_e32 v122, 16, v123
	v_and_b32_e32 v123, 0xffff0000, v123
	s_and_saveexec_b64 s[26:27], s[46:47]
	s_xor_b64 s[26:27], exec, s[26:27]
	v_pk_mul_f32 v[92:93], v[0:1], v[122:123] op_sel_hi:[0,1]
	v_pk_mul_f32 v[134:135], v[0:1], v[136:137] op_sel_hi:[0,1]
	s_andn2_saveexec_b64 vcc, s[26:27]
	v_lshlrev_b32_e32 v92, 16, v112
	v_and_b32_e32 v93, 0xffff0000, v112
	v_pk_mul_f32 v[134:135], v[0:1], v[92:93] op_sel_hi:[0,1]
	v_lshlrev_b32_e32 v92, 16, v113
	v_and_b32_e32 v93, 0xffff0000, v113
	v_pk_mul_f32 v[90:91], v[132:133], v[122:123] op_sel_hi:[0,1]
	v_pk_mul_f32 v[110:111], v[132:133], v[136:137] op_sel_hi:[0,1]
	v_pk_mul_f32 v[92:93], v[0:1], v[92:93] op_sel_hi:[0,1]
	s_or_b64 exec, exec, vcc

; __device__ __forceinline__ float bf_lo(unsigned w) { return __uint_as_float(w << 16); }
; __device__ __forceinline__ float bf_hi(unsigned w) { return __uint_as_float(w & 0xffff0000u); }
;     __device__ __forceinline__ void operator()(const f32x4 (&acc)[2][2][4][2], const Unit& u, int wr, int wc, int fr_in, int fq_in, PG8_LAS unsigned char* lds, int tid_in, int quad = -1) const {
;     ...
;                     const f32x4 w0 = *(const f32x4*)(cw + col + 4 * hf), w1 = *(const f32x4*)(cw + DFF + col + 4 * hf), w2 = *(const f32x4*)(cw + 2 * DFF + col + 4 * hf);
;                     float cur[4], p1[4], p2[4];
; #pragma unroll
;                     for (int k = 0; k < 4; ++k) { cur[k] = acc[ai][0][m][hf][k] * sc;
;                         p1[k] = __int_as_float(__builtin_amdgcn_update_dpp(__float_as_int(cur[k]), __float_as_int(cur[k]), 0x111, 0xf, 0xf, false));
;                         p2[k] = __int_as_float(__builtin_amdgcn_update_dpp(__float_as_int(cur[k]), __float_as_int(cur[k]), 0x112, 0xf, 0xf, false)); }
;                     if (fr < 2) {
;                         const float e0 = bf_lo(h1[2 * hf]), e1 = bf_hi(h1[2 * hf]), e2 = bf_lo(h1[2 * hf + 1]), e3 = bf_hi(h1[2 * hf + 1]);
;                         if (fr == 0) {
;                             p1[0] = e0 * sc1; p1[1] = e1 * sc1; p1[2] = e2 * sc1; p1[3] = e3 * sc1;
;                             p2[0] = bf_lo(h0[2 * hf]) * sc2; p2[1] = bf_hi(h0[2 * hf]) * sc2; p2[2] = bf_lo(h0[2 * hf + 1]) * sc2; p2[3] = bf_hi(h0[2 * hf + 1]) * sc2;
;                         } else { p2[0] = e0 * sc2; p2[1] = e1 * sc2; p2[2] = e2 * sc2; p2[3] = e3 * sc2; }
.LBB0_709:
	s_or_b64 exec, exec, s[50:51]
	global_load_dwordx4 v[90:93], v[170:171], off
	global_load_dwordx4 v[86:89], v[172:173], off
	global_load_dwordx4 v[82:85], v[174:175], off
	s_waitcnt lgkmcnt(2)
	v_mul_f32_e32 v125, v78, v117
	v_mul_f32_e32 v124, v79, v117
	v_mul_f32_e32 v123, v80, v117
	v_mul_f32_e32 v122, v81, v117
	v_mov_b32_dpp v110, v125 row_shr:1 row_mask:0xf bank_mask:0xf
	v_mov_b32_dpp v114, v125 row_shr:2 row_mask:0xf bank_mask:0xf
	v_mov_b32_dpp v111, v124 row_shr:1 row_mask:0xf bank_mask:0xf
	v_mov_b32_dpp v115, v124 row_shr:2 row_mask:0xf bank_mask:0xf
	v_mov_b32_dpp v108, v123 row_shr:1 row_mask:0xf bank_mask:0xf
	v_mov_b32_dpp v112, v123 row_shr:2 row_mask:0xf bank_mask:0xf
	v_mov_b32_dpp v109, v122 row_shr:1 row_mask:0xf bank_mask:0xf
	v_mov_b32_dpp v113, v122 row_shr:2 row_mask:0xf bank_mask:0xf
	s_and_saveexec_b64 s[24:25], s[44:45]
	s_cbranch_execz .LBB0_715
	s_waitcnt lgkmcnt(1)
	v_lshlrev_b32_e32 v78, 16, v104
	v_and_b32_e32 v79, 0xffff0000, v104
	v_lshlrev_b32_e32 v80, 16, v105
	v_and_b32_e32 v81, 0xffff0000, v105
	s_and_saveexec_b64 s[26:27], s[46:47]
	s_xor_b64 s[26:27], exec, s[26:27]
	s_cbranch_execz .LBB0_712
	s_waitcnt lgkmcnt(0)
	v_pk_mul_f32 v[112:113], v[0:1], v[80:81] op_sel_hi:[0,1]
	v_pk_mul_f32 v[114:115], v[0:1], v[78:79] op_sel_hi:[0,1]

; __device__ __forceinline__ float bf_lo(unsigned w) { return __uint_as_float(w << 16); }
; __device__ __forceinline__ float bf_hi(unsigned w) { return __uint_as_float(w & 0xffff0000u); }
;     __device__ __forceinline__ void operator()(const f32x4 (&acc)[2][2][4][2], const Unit& u, int wr, int wc, int fr_in, int fq_in, PG8_LAS unsigned char* lds, int tid_in, int quad = -1) const {
;     ...
;                     const f32x4 w0 = *(const f32x4*)(cw + col + 4 * hf), w1 = *(const f32x4*)(cw + DFF + col + 4 * hf), w2 = *(const f32x4*)(cw + 2 * DFF + col + 4 * hf);
;                     float cur[4], p1[4], p2[4];
; #pragma unroll
;                     for (int k = 0; k < 4; ++k) { cur[k] = acc[ai][0][m][hf][k] * sc;
;                         p1[k] = __int_as_float(__builtin_amdgcn_update_dpp(__float_as_int(cur[k]), __float_as_int(cur[k]), 0x111, 0xf, 0xf, false));
;                         p2[k] = __int_as_float(__builtin_amdgcn_update_dpp(__float_as_int(cur[k]), __float_as_int(cur[k]), 0x112, 0xf, 0xf, false)); }
;                     if (fr < 2) {
;                         const float e0 = bf_lo(h1[2 * hf]), e1 = bf_hi(h1[2 * hf]), e2 = bf_lo(h1[2 * hf + 1]), e3 = bf_hi(h1[2 * hf + 1]);
;                         if (fr == 0) {
;                             p1[0] = e0 * sc1; p1[1] = e1 * sc1; p1[2] = e2 * sc1; p1[3] = e3 * sc1;
;                             p2[0] = bf_lo(h0[2 * hf]) * sc2; p2[1] = bf_hi(h0[2 * hf]) * sc2; p2[2] = bf_lo(h0[2 * hf + 1]) * sc2; p2[3] = bf_hi(h0[2 * hf + 1]) * sc2;
;                         } else { p2[0] = e0 * sc2; p2[1] = e1 * sc2; p2[2] = e2 * sc2; p2[3] = e3 * sc2; }
.LBB0_715:
	s_or_b64 exec, exec, s[24:25]
	s_waitcnt lgkmcnt(1)
	global_load_dwordx4 v[102:105], v[170:171], off offset:16
	global_load_dwordx4 v[98:101], v[172:173], off offset:16
	global_load_dwordx4 v[78:81], v[174:175], off offset:16
	v_mul_f32_e32 v130, v74, v117
	v_mul_f32_e32 v129, v75, v117
	v_mul_f32_e32 v128, v76, v117
	v_mul_f32_e32 v127, v77, v117
	s_waitcnt lgkmcnt(0)
	v_mov_b32_dpp v94, v130 row_shr:1 row_mask:0xf bank_mask:0xf
	v_mov_b32_dpp v118, v130 row_shr:2 row_mask:0xf bank_mask:0xf
	v_mov_b32_dpp v95, v129 row_shr:1 row_mask:0xf bank_mask:0xf
	v_mov_b32_dpp v119, v129 row_shr:2 row_mask:0xf bank_mask:0xf
	v_mov_b32_dpp v74, v128 row_shr:1 row_mask:0xf bank_mask:0xf
	v_mov_b32_dpp v76, v128 row_shr:2 row_mask:0xf bank_mask:0xf
	v_mov_b32_dpp v75, v127 row_shr:1 row_mask:0xf bank_mask:0xf
	v_mov_b32_dpp v77, v127 row_shr:2 row_mask:0xf bank_mask:0xf
	s_and_saveexec_b64 s[24:25], s[44:45]
	s_cbranch_execz .LBB0_721
	v_lshlrev_b32_e32 v120, 16, v106
	v_and_b32_e32 v121, 0xffff0000, v106
	v_lshlrev_b32_e32 v106, 16, v107
	v_and_b32_e32 v107, 0xffff0000, v107
	s_and_saveexec_b64 s[26:27], s[46:47]
	s_xor_b64 s[26:27], exec, s[26:27]
	v_pk_mul_f32 v[76:77], v[0:1], v[106:107] op_sel_hi:[0,1]
	v_pk_mul_f32 v[118:119], v[0:1], v[120:121] op_sel_hi:[0,1]
	s_andn2_saveexec_b64 s[50:51], s[26:27]
	v_lshlrev_b32_e32 v76, 16, v96
	v_and_b32_e32 v77, 0xffff0000, v96
	v_pk_mul_f32 v[118:119], v[0:1], v[76:77] op_sel_hi:[0,1]
	v_lshlrev_b32_e32 v76, 16, v97
	v_and_b32_e32 v77, 0xffff0000, v97
	v_pk_mul_f32 v[74:75], v[116:117], v[106:107] op_sel_hi:[0,1]
	v_pk_mul_f32 v[94:95], v[116:117], v[120:121] op_sel_hi:[0,1]
	v_pk_mul_f32 v[76:77], v[0:1], v[76:77] op_sel_hi:[0,1]
	s_or_b64 exec, exec, s[50:51]

; __device__ __forceinline__ float bf_lo(unsigned w) { return __uint_as_float(w << 16); }
; __device__ __forceinline__ float bf_hi(unsigned w) { return __uint_as_float(w & 0xffff0000u); }
;     __device__ __forceinline__ void operator()(const f32x4 (&acc)[2][2][4][2], const Unit& u, int wr, int wc, int fr_in, int fq_in, PG8_LAS unsigned char* lds, int tid_in, int quad = -1) const {
;     ...
;                     const f32x4 w0 = *(const f32x4*)(cw + col + 4 * hf), w1 = *(const f32x4*)(cw + DFF + col + 4 * hf), w2 = *(const f32x4*)(cw + 2 * DFF + col + 4 * hf);
;                     float cur[4], p1[4], p2[4];
; #pragma unroll
;                     for (int k = 0; k < 4; ++k) { cur[k] = acc[ai][0][m][hf][k] * sc;
;                         p1[k] = __int_as_float(__builtin_amdgcn_update_dpp(__float_as_int(cur[k]), __float_as_int(cur[k]), 0x111, 0xf, 0xf, false));
;                         p2[k] = __int_as_float(__builtin_amdgcn_update_dpp(__float_as_int(cur[k]), __float_as_int(cur[k]), 0x112, 0xf, 0xf, false)); }
;                     if (fr < 2) {
;                         const float e0 = bf_lo(h1[2 * hf]), e1 = bf_hi(h1[2 * hf]), e2 = bf_lo(h1[2 * hf + 1]), e3 = bf_hi(h1[2 * hf + 1]);
;                         if (fr == 0) {
;                             p1[0] = e0 * sc1; p1[1] = e1 * sc1; p1[2] = e2 * sc1; p1[3] = e3 * sc1;
;                             p2[0] = bf_lo(h0[2 * hf]) * sc2; p2[1] = bf_hi(h0[2 * hf]) * sc2; p2[2] = bf_lo(h0[2 * hf + 1]) * sc2; p2[3] = bf_hi(h0[2 * hf + 1]) * sc2;
;                         } else { p2[0] = e0 * sc2; p2[1] = e1 * sc2; p2[2] = e2 * sc2; p2[3] = e3 * sc2; }
.LBB0_728:
	s_or_b64 exec, exec, s[24:25]
	global_load_dwordx4 v[74:77], v[170:171], off
	global_load_dwordx4 v[70:73], v[172:173], off
	global_load_dwordx4 v[66:69], v[174:175], off
	s_waitcnt lgkmcnt(2)
	v_mul_f32_e32 v109, v62, v101
	v_mul_f32_e32 v108, v63, v101
	v_mul_f32_e32 v107, v64, v101
	v_mul_f32_e32 v106, v65, v101
	v_mov_b32_dpp v94, v109 row_shr:1 row_mask:0xf bank_mask:0xf
	v_mov_b32_dpp v98, v109 row_shr:2 row_mask:0xf bank_mask:0xf
	v_mov_b32_dpp v95, v108 row_shr:1 row_mask:0xf bank_mask:0xf
	v_mov_b32_dpp v99, v108 row_shr:2 row_mask:0xf bank_mask:0xf
	v_mov_b32_dpp v92, v107 row_shr:1 row_mask:0xf bank_mask:0xf
	v_mov_b32_dpp v96, v107 row_shr:2 row_mask:0xf bank_mask:0xf
	v_mov_b32_dpp v93, v106 row_shr:1 row_mask:0xf bank_mask:0xf
	v_mov_b32_dpp v97, v106 row_shr:2 row_mask:0xf bank_mask:0xf
	s_and_saveexec_b64 s[24:25], s[44:45]
	s_cbranch_execz .LBB0_734
	s_waitcnt lgkmcnt(1)
	v_lshlrev_b32_e32 v62, 16, v88
	v_and_b32_e32 v63, 0xffff0000, v88
	v_lshlrev_b32_e32 v64, 16, v89
	v_and_b32_e32 v65, 0xffff0000, v89
	s_and_saveexec_b64 s[26:27], s[46:47]
	s_xor_b64 s[26:27], exec, s[26:27]
	s_cbranch_execz .LBB0_731
	s_waitcnt lgkmcnt(0)
	v_pk_mul_f32 v[96:97], v[0:1], v[64:65] op_sel_hi:[0,1]
	v_pk_mul_f32 v[98:99], v[0:1], v[62:63] op_sel_hi:[0,1]

; __device__ __forceinline__ float bf_lo(unsigned w) { return __uint_as_float(w << 16); }
; __device__ __forceinline__ float bf_hi(unsigned w) { return __uint_as_float(w & 0xffff0000u); }
;     __device__ __forceinline__ void operator()(const f32x4 (&acc)[2][2][4][2], const Unit& u, int wr, int wc, int fr_in, int fq_in, PG8_LAS unsigned char* lds, int tid_in, int quad = -1) const {
;     ...
;                     const f32x4 w0 = *(const f32x4*)(cw + col + 4 * hf), w1 = *(const f32x4*)(cw + DFF + col + 4 * hf), w2 = *(const f32x4*)(cw + 2 * DFF + col + 4 * hf);
;                     float cur[4], p1[4], p2[4];
; #pragma unroll
;                     for (int k = 0; k < 4; ++k) { cur[k] = acc[ai][0][m][hf][k] * sc;
;                         p1[k] = __int_as_float(__builtin_amdgcn_update_dpp(__float_as_int(cur[k]), __float_as_int(cur[k]), 0x111, 0xf, 0xf, false));
;                         p2[k] = __int_as_float(__builtin_amdgcn_update_dpp(__float_as_int(cur[k]), __float_as_int(cur[k]), 0x112, 0xf, 0xf, false)); }
;                     if (fr < 2) {
;                         const float e0 = bf_lo(h1[2 * hf]), e1 = bf_hi(h1[2 * hf]), e2 = bf_lo(h1[2 * hf + 1]), e3 = bf_hi(h1[2 * hf + 1]);
;                         if (fr == 0) {
;                             p1[0] = e0 * sc1; p1[1] = e1 * sc1; p1[2] = e2 * sc1; p1[3] = e3 * sc1;
;                             p2[0] = bf_lo(h0[2 * hf]) * sc2; p2[1] = bf_hi(h0[2 * hf]) * sc2; p2[2] = bf_lo(h0[2 * hf + 1]) * sc2; p2[3] = bf_hi(h0[2 * hf + 1]) * sc2;
;                         } else { p2[0] = e0 * sc2; p2[1] = e1 * sc2; p2[2] = e2 * sc2; p2[3] = e3 * sc2; }
.LBB0_734:
	s_or_b64 exec, exec, s[24:25]
	s_waitcnt lgkmcnt(1)
	global_load_dwordx4 v[86:89], v[170:171], off offset:16
	global_load_dwordx4 v[82:85], v[172:173], off offset:16
	global_load_dwordx4 v[62:65], v[174:175], off offset:16
	v_mul_f32_e32 v114, v58, v101
	v_mul_f32_e32 v113, v59, v101
	v_mul_f32_e32 v112, v60, v101
	v_mul_f32_e32 v111, v61, v101
	s_waitcnt lgkmcnt(0)
	v_mov_b32_dpp v78, v114 row_shr:1 row_mask:0xf bank_mask:0xf
	v_mov_b32_dpp v102, v114 row_shr:2 row_mask:0xf bank_mask:0xf
	v_mov_b32_dpp v79, v113 row_shr:1 row_mask:0xf bank_mask:0xf
	v_mov_b32_dpp v103, v113 row_shr:2 row_mask:0xf bank_mask:0xf
	v_mov_b32_dpp v58, v112 row_shr:1 row_mask:0xf bank_mask:0xf
	v_mov_b32_dpp v60, v112 row_shr:2 row_mask:0xf bank_mask:0xf
	v_mov_b32_dpp v59, v111 row_shr:1 row_mask:0xf bank_mask:0xf
	v_mov_b32_dpp v61, v111 row_shr:2 row_mask:0xf bank_mask:0xf
	s_and_saveexec_b64 s[24:25], s[44:45]
	s_cbranch_execz .LBB0_740
	v_lshlrev_b32_e32 v104, 16, v90
	v_and_b32_e32 v105, 0xffff0000, v90
	v_lshlrev_b32_e32 v90, 16, v91
	v_and_b32_e32 v91, 0xffff0000, v91
	s_and_saveexec_b64 s[26:27], s[46:47]
	s_xor_b64 s[26:27], exec, s[26:27]
	v_pk_mul_f32 v[60:61], v[0:1], v[90:91] op_sel_hi:[0,1]
	v_pk_mul_f32 v[102:103], v[0:1], v[104:105] op_sel_hi:[0,1]
	s_andn2_saveexec_b64 s[50:51], s[26:27]
	v_lshlrev_b32_e32 v60, 16, v80
	v_and_b32_e32 v61, 0xffff0000, v80
	v_pk_mul_f32 v[102:103], v[0:1], v[60:61] op_sel_hi:[0,1]
	v_lshlrev_b32_e32 v60, 16, v81
	v_and_b32_e32 v61, 0xffff0000, v81
	v_pk_mul_f32 v[58:59], v[100:101], v[90:91] op_sel_hi:[0,1]
	v_pk_mul_f32 v[78:79], v[100:101], v[104:105] op_sel_hi:[0,1]
	v_pk_mul_f32 v[60:61], v[0:1], v[60:61] op_sel_hi:[0,1]
	s_or_b64 exec, exec, s[50:51]

; __device__ __forceinline__ float bf_lo(unsigned w) { return __uint_as_float(w << 16); }
; __device__ __forceinline__ float bf_hi(unsigned w) { return __uint_as_float(w & 0xffff0000u); }
;     __device__ __forceinline__ void operator()(const f32x4 (&acc)[2][2][4][2], const Unit& u, int wr, int wc, int fr_in, int fq_in, PG8_LAS unsigned char* lds, int tid_in, int quad = -1) const {
;     ...
;                     const f32x4 w0 = *(const f32x4*)(cw + col + 4 * hf), w1 = *(const f32x4*)(cw + DFF + col + 4 * hf), w2 = *(const f32x4*)(cw + 2 * DFF + col + 4 * hf);
;                     float cur[4], p1[4], p2[4];
; #pragma unroll
;                     for (int k = 0; k < 4; ++k) { cur[k] = acc[ai][0][m][hf][k] * sc;
;                         p1[k] = __int_as_float(__builtin_amdgcn_update_dpp(__float_as_int(cur[k]), __float_as_int(cur[k]), 0x111, 0xf, 0xf, false));
;                         p2[k] = __int_as_float(__builtin_amdgcn_update_dpp(__float_as_int(cur[k]), __float_as_int(cur[k]), 0x112, 0xf, 0xf, false)); }
;                     if (fr < 2) {
;                         const float e0 = bf_lo(h1[2 * hf]), e1 = bf_hi(h1[2 * hf]), e2 = bf_lo(h1[2 * hf + 1]), e3 = bf_hi(h1[2 * hf + 1]);
;                         if (fr == 0) {
;                             p1[0] = e0 * sc1; p1[1] = e1 * sc1; p1[2] = e2 * sc1; p1[3] = e3 * sc1;
;                             p2[0] = bf_lo(h0[2 * hf]) * sc2; p2[1] = bf_hi(h0[2 * hf]) * sc2; p2[2] = bf_lo(h0[2 * hf + 1]) * sc2; p2[3] = bf_hi(h0[2 * hf + 1]) * sc2;
;                         } else { p2[0] = e0 * sc2; p2[1] = e1 * sc2; p2[2] = e2 * sc2; p2[3] = e3 * sc2; }
.LBB0_747:
	s_or_b64 exec, exec, s[50:51]
	global_load_dwordx4 v[58:61], v[170:171], off
	global_load_dwordx4 v[54:57], v[172:173], off
	global_load_dwordx4 v[50:53], v[174:175], off
	s_waitcnt lgkmcnt(2)
	v_mul_f32_e32 v93, v46, v85
	v_mul_f32_e32 v92, v47, v85
	v_mul_f32_e32 v91, v48, v85
	v_mul_f32_e32 v90, v49, v85
	v_mov_b32_dpp v78, v93 row_shr:1 row_mask:0xf bank_mask:0xf
	v_mov_b32_dpp v82, v93 row_shr:2 row_mask:0xf bank_mask:0xf
	v_mov_b32_dpp v79, v92 row_shr:1 row_mask:0xf bank_mask:0xf
	v_mov_b32_dpp v83, v92 row_shr:2 row_mask:0xf bank_mask:0xf
	v_mov_b32_dpp v76, v91 row_shr:1 row_mask:0xf bank_mask:0xf
	v_mov_b32_dpp v80, v91 row_shr:2 row_mask:0xf bank_mask:0xf
	v_mov_b32_dpp v77, v90 row_shr:1 row_mask:0xf bank_mask:0xf
	v_mov_b32_dpp v81, v90 row_shr:2 row_mask:0xf bank_mask:0xf
	s_and_saveexec_b64 s[50:51], s[44:45]
	s_cbranch_execz .LBB0_753
	s_waitcnt lgkmcnt(1)
	v_lshlrev_b32_e32 v46, 16, v72
	v_and_b32_e32 v47, 0xffff0000, v72
	v_lshlrev_b32_e32 v48, 16, v73
	v_and_b32_e32 v49, 0xffff0000, v73
	s_and_saveexec_b64 s[26:27], s[46:47]
	s_xor_b64 s[26:27], exec, s[26:27]
	s_cbranch_execz .LBB0_750
	s_waitcnt lgkmcnt(0)
	v_pk_mul_f32 v[80:81], v[0:1], v[48:49] op_sel_hi:[0,1]
	v_pk_mul_f32 v[82:83], v[0:1], v[46:47] op_sel_hi:[0,1]

; __device__ __forceinline__ float bf_lo(unsigned w) { return __uint_as_float(w << 16); }
; __device__ __forceinline__ float bf_hi(unsigned w) { return __uint_as_float(w & 0xffff0000u); }
;     __device__ __forceinline__ void operator()(const f32x4 (&acc)[2][2][4][2], const Unit& u, int wr, int wc, int fr_in, int fq_in, PG8_LAS unsigned char* lds, int tid_in, int quad = -1) const {
;     ...
;                     const f32x4 w0 = *(const f32x4*)(cw + col + 4 * hf), w1 = *(const f32x4*)(cw + DFF + col + 4 * hf), w2 = *(const f32x4*)(cw + 2 * DFF + col + 4 * hf);
;                     float cur[4], p1[4], p2[4];
; #pragma unroll
;                     for (int k = 0; k < 4; ++k) { cur[k] = acc[ai][0][m][hf][k] * sc;
;                         p1[k] = __int_as_float(__builtin_amdgcn_update_dpp(__float_as_int(cur[k]), __float_as_int(cur[k]), 0x111, 0xf, 0xf, false));
;                         p2[k] = __int_as_float(__builtin_amdgcn_update_dpp(__float_as_int(cur[k]), __float_as_int(cur[k]), 0x112, 0xf, 0xf, false)); }
;                     if (fr < 2) {
;                         const float e0 = bf_lo(h1[2 * hf]), e1 = bf_hi(h1[2 * hf]), e2 = bf_lo(h1[2 * hf + 1]), e3 = bf_hi(h1[2 * hf + 1]);
;                         if (fr == 0) {
;                             p1[0] = e0 * sc1; p1[1] = e1 * sc1; p1[2] = e2 * sc1; p1[3] = e3 * sc1;
;                             p2[0] = bf_lo(h0[2 * hf]) * sc2; p2[1] = bf_hi(h0[2 * hf]) * sc2; p2[2] = bf_lo(h0[2 * hf + 1]) * sc2; p2[3] = bf_hi(h0[2 * hf + 1]) * sc2;
;                         } else { p2[0] = e0 * sc2; p2[1] = e1 * sc2; p2[2] = e2 * sc2; p2[3] = e3 * sc2; }
.LBB0_753:
	s_or_b64 exec, exec, s[50:51]
	s_waitcnt lgkmcnt(1)
	global_load_dwordx4 v[70:73], v[170:171], off offset:16
	global_load_dwordx4 v[66:69], v[172:173], off offset:16
	global_load_dwordx4 v[46:49], v[174:175], off offset:16
	v_mul_f32_e32 v98, v42, v85
	v_mul_f32_e32 v97, v43, v85
	v_mul_f32_e32 v96, v44, v85
	v_mul_f32_e32 v95, v45, v85
	s_waitcnt lgkmcnt(0)
	v_mov_b32_dpp v62, v98 row_shr:1 row_mask:0xf bank_mask:0xf
	v_mov_b32_dpp v86, v98 row_shr:2 row_mask:0xf bank_mask:0xf
	v_mov_b32_dpp v63, v97 row_shr:1 row_mask:0xf bank_mask:0xf
	v_mov_b32_dpp v87, v97 row_shr:2 row_mask:0xf bank_mask:0xf
	v_mov_b32_dpp v42, v96 row_shr:1 row_mask:0xf bank_mask:0xf
	v_mov_b32_dpp v44, v96 row_shr:2 row_mask:0xf bank_mask:0xf
	v_mov_b32_dpp v43, v95 row_shr:1 row_mask:0xf bank_mask:0xf
	v_mov_b32_dpp v45, v95 row_shr:2 row_mask:0xf bank_mask:0xf
	s_and_saveexec_b64 s[50:51], s[44:45]
	s_cbranch_execz .LBB0_759
	v_lshlrev_b32_e32 v88, 16, v74
	v_and_b32_e32 v89, 0xffff0000, v74
	v_lshlrev_b32_e32 v74, 16, v75
	v_and_b32_e32 v75, 0xffff0000, v75
	s_and_saveexec_b64 s[26:27], s[46:47]
	s_xor_b64 s[26:27], exec, s[26:27]
	v_pk_mul_f32 v[44:45], v[0:1], v[74:75] op_sel_hi:[0,1]
	v_pk_mul_f32 v[86:87], v[0:1], v[88:89] op_sel_hi:[0,1]
	s_andn2_saveexec_b64 vcc, s[26:27]
	v_lshlrev_b32_e32 v44, 16, v64
	v_and_b32_e32 v45, 0xffff0000, v64
	v_pk_mul_f32 v[86:87], v[0:1], v[44:45] op_sel_hi:[0,1]
	v_lshlrev_b32_e32 v44, 16, v65
	v_and_b32_e32 v45, 0xffff0000, v65
	v_pk_mul_f32 v[42:43], v[84:85], v[74:75] op_sel_hi:[0,1]
	v_pk_mul_f32 v[62:63], v[84:85], v[88:89] op_sel_hi:[0,1]
	v_pk_mul_f32 v[44:45], v[0:1], v[44:45] op_sel_hi:[0,1]
	s_or_b64 exec, exec, vcc

; __device__ __forceinline__ float bf_lo(unsigned w) { return __uint_as_float(w << 16); }
; __device__ __forceinline__ float bf_hi(unsigned w) { return __uint_as_float(w & 0xffff0000u); }
;     __device__ __forceinline__ void operator()(const f32x4 (&acc)[2][2][4][2], const Unit& u, int wr, int wc, int fr_in, int fq_in, PG8_LAS unsigned char* lds, int tid_in, int quad = -1) const {
;     ...
;                     const f32x4 w0 = *(const f32x4*)(cw + col + 4 * hf), w1 = *(const f32x4*)(cw + DFF + col + 4 * hf), w2 = *(const f32x4*)(cw + 2 * DFF + col + 4 * hf);
;                     float cur[4], p1[4], p2[4];
; #pragma unroll
;                     for (int k = 0; k < 4; ++k) { cur[k] = acc[ai][0][m][hf][k] * sc;
;                         p1[k] = __int_as_float(__builtin_amdgcn_update_dpp(__float_as_int(cur[k]), __float_as_int(cur[k]), 0x111, 0xf, 0xf, false));
;                         p2[k] = __int_as_float(__builtin_amdgcn_update_dpp(__float_as_int(cur[k]), __float_as_int(cur[k]), 0x112, 0xf, 0xf, false)); }
;                     if (fr < 2) {
;                         const float e0 = bf_lo(h1[2 * hf]), e1 = bf_hi(h1[2 * hf]), e2 = bf_lo(h1[2 * hf + 1]), e3 = bf_hi(h1[2 * hf + 1]);
;                         if (fr == 0) {
;                             p1[0] = e0 * sc1; p1[1] = e1 * sc1; p1[2] = e2 * sc1; p1[3] = e3 * sc1;
;                             p2[0] = bf_lo(h0[2 * hf]) * sc2; p2[1] = bf_hi(h0[2 * hf]) * sc2; p2[2] = bf_lo(h0[2 * hf + 1]) * sc2; p2[3] = bf_hi(h0[2 * hf + 1]) * sc2;
;                         } else { p2[0] = e0 * sc2; p2[1] = e1 * sc2; p2[2] = e2 * sc2; p2[3] = e3 * sc2; }
.LBB0_766:
	s_or_b64 exec, exec, s[50:51]
	global_load_dwordx4 v[42:45], v[170:171], off
	global_load_dwordx4 v[38:41], v[172:173], off
	global_load_dwordx4 v[34:37], v[174:175], off
	s_waitcnt lgkmcnt(2)
	v_mul_f32_e32 v77, v30, v69
	v_mul_f32_e32 v76, v31, v69
	v_mul_f32_e32 v75, v32, v69
	v_mul_f32_e32 v74, v33, v69
	v_mov_b32_dpp v62, v77 row_shr:1 row_mask:0xf bank_mask:0xf
	v_mov_b32_dpp v66, v77 row_shr:2 row_mask:0xf bank_mask:0xf
	v_mov_b32_dpp v63, v76 row_shr:1 row_mask:0xf bank_mask:0xf
	v_mov_b32_dpp v67, v76 row_shr:2 row_mask:0xf bank_mask:0xf
	v_mov_b32_dpp v60, v75 row_shr:1 row_mask:0xf bank_mask:0xf
	v_mov_b32_dpp v64, v75 row_shr:2 row_mask:0xf bank_mask:0xf
	v_mov_b32_dpp v61, v74 row_shr:1 row_mask:0xf bank_mask:0xf
	v_mov_b32_dpp v65, v74 row_shr:2 row_mask:0xf bank_mask:0xf
	s_and_saveexec_b64 s[50:51], s[44:45]
	s_cbranch_execz .LBB0_772
	s_waitcnt lgkmcnt(1)
	v_lshlrev_b32_e32 v30, 16, v56
	v_and_b32_e32 v31, 0xffff0000, v56
	v_lshlrev_b32_e32 v32, 16, v57
	v_and_b32_e32 v33, 0xffff0000, v57
	s_and_saveexec_b64 s[26:27], s[46:47]
	s_xor_b64 s[26:27], exec, s[26:27]
	s_cbranch_execz .LBB0_769
	s_waitcnt lgkmcnt(0)
	v_pk_mul_f32 v[64:65], v[0:1], v[32:33] op_sel_hi:[0,1]
	v_pk_mul_f32 v[66:67], v[0:1], v[30:31] op_sel_hi:[0,1]

; __device__ __forceinline__ float bf_lo(unsigned w) { return __uint_as_float(w << 16); }
; __device__ __forceinline__ float bf_hi(unsigned w) { return __uint_as_float(w & 0xffff0000u); }
;     __device__ __forceinline__ void operator()(const f32x4 (&acc)[2][2][4][2], const Unit& u, int wr, int wc, int fr_in, int fq_in, PG8_LAS unsigned char* lds, int tid_in, int quad = -1) const {
;     ...
;                     const f32x4 w0 = *(const f32x4*)(cw + col + 4 * hf), w1 = *(const f32x4*)(cw + DFF + col + 4 * hf), w2 = *(const f32x4*)(cw + 2 * DFF + col + 4 * hf);
;                     float cur[4], p1[4], p2[4];
; #pragma unroll
;                     for (int k = 0; k < 4; ++k) { cur[k] = acc[ai][0][m][hf][k] * sc;
;                         p1[k] = __int_as_float(__builtin_amdgcn_update_dpp(__float_as_int(cur[k]), __float_as_int(cur[k]), 0x111, 0xf, 0xf, false));
;                         p2[k] = __int_as_float(__builtin_amdgcn_update_dpp(__float_as_int(cur[k]), __float_as_int(cur[k]), 0x112, 0xf, 0xf, false)); }
;                     if (fr < 2) {
;                         const float e0 = bf_lo(h1[2 * hf]), e1 = bf_hi(h1[2 * hf]), e2 = bf_lo(h1[2 * hf + 1]), e3 = bf_hi(h1[2 * hf + 1]);
;                         if (fr == 0) {
;                             p1[0] = e0 * sc1; p1[1] = e1 * sc1; p1[2] = e2 * sc1; p1[3] = e3 * sc1;
;                             p2[0] = bf_lo(h0[2 * hf]) * sc2; p2[1] = bf_hi(h0[2 * hf]) * sc2; p2[2] = bf_lo(h0[2 * hf + 1]) * sc2; p2[3] = bf_hi(h0[2 * hf + 1]) * sc2;
;                         } else { p2[0] = e0 * sc2; p2[1] = e1 * sc2; p2[2] = e2 * sc2; p2[3] = e3 * sc2; }
.LBB0_772:
	s_or_b64 exec, exec, s[50:51]
	s_waitcnt lgkmcnt(1)
	global_load_dwordx4 v[54:57], v[170:171], off offset:16
	global_load_dwordx4 v[50:53], v[172:173], off offset:16
	global_load_dwordx4 v[30:33], v[174:175], off offset:16
	v_mul_f32_e32 v82, v26, v69
	v_mul_f32_e32 v81, v27, v69
	v_mul_f32_e32 v80, v28, v69
	v_mul_f32_e32 v79, v29, v69
	s_waitcnt lgkmcnt(0)
	v_mov_b32_dpp v46, v82 row_shr:1 row_mask:0xf bank_mask:0xf
	v_mov_b32_dpp v70, v82 row_shr:2 row_mask:0xf bank_mask:0xf
	v_mov_b32_dpp v47, v81 row_shr:1 row_mask:0xf bank_mask:0xf
	v_mov_b32_dpp v71, v81 row_shr:2 row_mask:0xf bank_mask:0xf
	v_mov_b32_dpp v26, v80 row_shr:1 row_mask:0xf bank_mask:0xf
	v_mov_b32_dpp v28, v80 row_shr:2 row_mask:0xf bank_mask:0xf
	v_mov_b32_dpp v27, v79 row_shr:1 row_mask:0xf bank_mask:0xf
	v_mov_b32_dpp v29, v79 row_shr:2 row_mask:0xf bank_mask:0xf
	s_and_saveexec_b64 s[50:51], s[44:45]
	s_cbranch_execz .LBB0_778
	v_lshlrev_b32_e32 v72, 16, v58
	v_and_b32_e32 v73, 0xffff0000, v58
	v_lshlrev_b32_e32 v58, 16, v59
	v_and_b32_e32 v59, 0xffff0000, v59
	s_and_saveexec_b64 s[26:27], s[46:47]
	s_xor_b64 s[26:27], exec, s[26:27]
	v_pk_mul_f32 v[28:29], v[0:1], v[58:59] op_sel_hi:[0,1]
	v_pk_mul_f32 v[70:71], v[0:1], v[72:73] op_sel_hi:[0,1]
	s_andn2_saveexec_b64 vcc, s[26:27]
	v_lshlrev_b32_e32 v28, 16, v48
	v_and_b32_e32 v29, 0xffff0000, v48
	v_pk_mul_f32 v[70:71], v[0:1], v[28:29] op_sel_hi:[0,1]
	v_lshlrev_b32_e32 v28, 16, v49
	v_and_b32_e32 v29, 0xffff0000, v49
	v_pk_mul_f32 v[26:27], v[68:69], v[58:59] op_sel_hi:[0,1]
	v_pk_mul_f32 v[46:47], v[68:69], v[72:73] op_sel_hi:[0,1]
	v_pk_mul_f32 v[28:29], v[0:1], v[28:29] op_sel_hi:[0,1]
	s_or_b64 exec, exec, vcc

; __device__ __forceinline__ float bf_lo(unsigned w) { return __uint_as_float(w << 16); }
; __device__ __forceinline__ float bf_hi(unsigned w) { return __uint_as_float(w & 0xffff0000u); }
;     __device__ __forceinline__ void operator()(const f32x4 (&acc)[2][2][4][2], const Unit& u, int wr, int wc, int fr_in, int fq_in, PG8_LAS unsigned char* lds, int tid_in, int quad = -1) const {
;     ...
;                     const f32x4 w0 = *(const f32x4*)(cw + col + 4 * hf), w1 = *(const f32x4*)(cw + DFF + col + 4 * hf), w2 = *(const f32x4*)(cw + 2 * DFF + col + 4 * hf);
;                     float cur[4], p1[4], p2[4];
; #pragma unroll
;                     for (int k = 0; k < 4; ++k) { cur[k] = acc[ai][0][m][hf][k] * sc;
;                         p1[k] = __int_as_float(__builtin_amdgcn_update_dpp(__float_as_int(cur[k]), __float_as_int(cur[k]), 0x111, 0xf, 0xf, false));
;                         p2[k] = __int_as_float(__builtin_amdgcn_update_dpp(__float_as_int(cur[k]), __float_as_int(cur[k]), 0x112, 0xf, 0xf, false)); }
;                     if (fr < 2) {
;                         const float e0 = bf_lo(h1[2 * hf]), e1 = bf_hi(h1[2 * hf]), e2 = bf_lo(h1[2 * hf + 1]), e3 = bf_hi(h1[2 * hf + 1]);
;                         if (fr == 0) {
;                             p1[0] = e0 * sc1; p1[1] = e1 * sc1; p1[2] = e2 * sc1; p1[3] = e3 * sc1;
;                             p2[0] = bf_lo(h0[2 * hf]) * sc2; p2[1] = bf_hi(h0[2 * hf]) * sc2; p2[2] = bf_lo(h0[2 * hf + 1]) * sc2; p2[3] = bf_hi(h0[2 * hf + 1]) * sc2;
;                         } else { p2[0] = e0 * sc2; p2[1] = e1 * sc2; p2[2] = e2 * sc2; p2[3] = e3 * sc2; }
.LBB0_785:
	s_or_b64 exec, exec, s[50:51]
	global_load_dwordx4 v[26:29], v[170:171], off
	global_load_dwordx4 v[22:25], v[172:173], off
	global_load_dwordx4 v[18:21], v[174:175], off
	s_waitcnt lgkmcnt(2)
	v_mul_f32_e32 v61, v14, v53
	v_mul_f32_e32 v60, v15, v53
	v_mul_f32_e32 v59, v16, v53
	v_mul_f32_e32 v58, v17, v53
	v_mov_b32_dpp v46, v61 row_shr:1 row_mask:0xf bank_mask:0xf
	v_mov_b32_dpp v50, v61 row_shr:2 row_mask:0xf bank_mask:0xf
	v_mov_b32_dpp v47, v60 row_shr:1 row_mask:0xf bank_mask:0xf
	v_mov_b32_dpp v51, v60 row_shr:2 row_mask:0xf bank_mask:0xf
	v_mov_b32_dpp v44, v59 row_shr:1 row_mask:0xf bank_mask:0xf
	v_mov_b32_dpp v48, v59 row_shr:2 row_mask:0xf bank_mask:0xf
	v_mov_b32_dpp v45, v58 row_shr:1 row_mask:0xf bank_mask:0xf
	v_mov_b32_dpp v49, v58 row_shr:2 row_mask:0xf bank_mask:0xf
	s_and_saveexec_b64 s[24:25], s[44:45]
	s_cbranch_execz .LBB0_791
	s_waitcnt lgkmcnt(1)
	v_lshlrev_b32_e32 v14, 16, v40
	v_and_b32_e32 v15, 0xffff0000, v40
	v_lshlrev_b32_e32 v16, 16, v41
	v_and_b32_e32 v17, 0xffff0000, v41
	s_and_saveexec_b64 s[26:27], s[46:47]
	s_xor_b64 s[26:27], exec, s[26:27]
	s_cbranch_execz .LBB0_788
	s_waitcnt lgkmcnt(0)
	v_pk_mul_f32 v[48:49], v[0:1], v[16:17] op_sel_hi:[0,1]
	v_pk_mul_f32 v[50:51], v[0:1], v[14:15] op_sel_hi:[0,1]

; __device__ __forceinline__ float bf_lo(unsigned w) { return __uint_as_float(w << 16); }
; __device__ __forceinline__ float bf_hi(unsigned w) { return __uint_as_float(w & 0xffff0000u); }
;     __device__ __forceinline__ void operator()(const f32x4 (&acc)[2][2][4][2], const Unit& u, int wr, int wc, int fr_in, int fq_in, PG8_LAS unsigned char* lds, int tid_in, int quad = -1) const {
;     ...
;                     const f32x4 w0 = *(const f32x4*)(cw + col + 4 * hf), w1 = *(const f32x4*)(cw + DFF + col + 4 * hf), w2 = *(const f32x4*)(cw + 2 * DFF + col + 4 * hf);
;                     float cur[4], p1[4], p2[4];
; #pragma unroll
;                     for (int k = 0; k < 4; ++k) { cur[k] = acc[ai][0][m][hf][k] * sc;
;                         p1[k] = __int_as_float(__builtin_amdgcn_update_dpp(__float_as_int(cur[k]), __float_as_int(cur[k]), 0x111, 0xf, 0xf, false));
;                         p2[k] = __int_as_float(__builtin_amdgcn_update_dpp(__float_as_int(cur[k]), __float_as_int(cur[k]), 0x112, 0xf, 0xf, false)); }
;                     if (fr < 2) {
;                         const float e0 = bf_lo(h1[2 * hf]), e1 = bf_hi(h1[2 * hf]), e2 = bf_lo(h1[2 * hf + 1]), e3 = bf_hi(h1[2 * hf + 1]);
;                         if (fr == 0) {
;                             p1[0] = e0 * sc1; p1[1] = e1 * sc1; p1[2] = e2 * sc1; p1[3] = e3 * sc1;
;                             p2[0] = bf_lo(h0[2 * hf]) * sc2; p2[1] = bf_hi(h0[2 * hf]) * sc2; p2[2] = bf_lo(h0[2 * hf + 1]) * sc2; p2[3] = bf_hi(h0[2 * hf + 1]) * sc2;
;                         } else { p2[0] = e0 * sc2; p2[1] = e1 * sc2; p2[2] = e2 * sc2; p2[3] = e3 * sc2; }
.LBB0_791:
	s_or_b64 exec, exec, s[24:25]
	s_waitcnt lgkmcnt(1)
	global_load_dwordx4 v[38:41], v[170:171], off offset:16
	global_load_dwordx4 v[34:37], v[172:173], off offset:16
	global_load_dwordx4 v[14:17], v[174:175], off offset:16
	v_mul_f32_e32 v66, v10, v53
	v_mul_f32_e32 v65, v11, v53
	v_mul_f32_e32 v64, v12, v53
	v_mul_f32_e32 v63, v13, v53
	s_waitcnt lgkmcnt(0)
	v_mov_b32_dpp v30, v66 row_shr:1 row_mask:0xf bank_mask:0xf
	v_mov_b32_dpp v54, v66 row_shr:2 row_mask:0xf bank_mask:0xf
	v_mov_b32_dpp v31, v65 row_shr:1 row_mask:0xf bank_mask:0xf
	v_mov_b32_dpp v55, v65 row_shr:2 row_mask:0xf bank_mask:0xf
	v_mov_b32_dpp v10, v64 row_shr:1 row_mask:0xf bank_mask:0xf
	v_mov_b32_dpp v12, v64 row_shr:2 row_mask:0xf bank_mask:0xf
	v_mov_b32_dpp v11, v63 row_shr:1 row_mask:0xf bank_mask:0xf
	v_mov_b32_dpp v13, v63 row_shr:2 row_mask:0xf bank_mask:0xf
	s_and_saveexec_b64 s[24:25], s[44:45]
	s_cbranch_execz .LBB0_797
	v_lshlrev_b32_e32 v56, 16, v42
	v_and_b32_e32 v57, 0xffff0000, v42
	v_lshlrev_b32_e32 v42, 16, v43
	v_and_b32_e32 v43, 0xffff0000, v43
	s_and_saveexec_b64 s[26:27], s[46:47]
	s_xor_b64 s[26:27], exec, s[26:27]
	v_pk_mul_f32 v[12:13], v[0:1], v[42:43] op_sel_hi:[0,1]
	v_pk_mul_f32 v[54:55], v[0:1], v[56:57] op_sel_hi:[0,1]
	s_andn2_saveexec_b64 s[44:45], s[26:27]
	v_lshlrev_b32_e32 v12, 16, v32
	v_and_b32_e32 v13, 0xffff0000, v32
	v_pk_mul_f32 v[54:55], v[0:1], v[12:13] op_sel_hi:[0,1]
	v_lshlrev_b32_e32 v12, 16, v33
	v_and_b32_e32 v13, 0xffff0000, v33
	v_pk_mul_f32 v[10:11], v[52:53], v[42:43] op_sel_hi:[0,1]
	v_pk_mul_f32 v[30:31], v[52:53], v[56:57] op_sel_hi:[0,1]
	v_pk_mul_f32 v[12:13], v[0:1], v[12:13] op_sel_hi:[0,1]
	s_or_b64 exec, exec, s[44:45]
